# loop-edge edit: attention rescale decision reduced from a six-branch ballot ladder to two scalar tests; on top of widened gate loads, arrival-counter barrier, attention staging edits
# speedup vs baseline: 1.0007x; 1.0004x over previous
.LBB0_301:
	s_nop 6
	v_max_f32_e32 v0, v161, v161
	v_max_f32_e32 v192, v160, v160
	v_max_f32_e32 v0, v192, v0
	v_max3_f32 v0, v0, v162, v163
	v_max3_f32 v0, v0, v164, v165
	v_max3_f32 v0, v0, v166, v167
	v_max3_f32 v0, v0, v168, v169
	v_max3_f32 v0, v0, v170, v171
	v_max3_f32 v0, v0, v172, v173
	v_max3_f32 v0, v0, v174, v175
	v_mov_b32_e32 v192, v0
	s_nop 1
	v_permlane32_swap_b32_e32 v0, v192
	v_max_f32_e32 v192, v192, v192
	v_max_f32_e32 v0, v0, v0
	v_max_f32_e32 v0, v0, v192
	s_cmp_eq_u32 s26, 0
	s_cselect_b64 s[30:31], -1, 0
	v_cmp_lt_f32_e32 vcc, s1, v0
	s_cbranch_scc1 .Lattn_resc0
	s_cmp_eq_u64 vcc, 0
	s_cbranch_scc1 .LBB0_307
.Lattn_resc0:
	v_cmp_lt_f32_e32 vcc, s1, v0
	s_or_b64 vcc, s[30:31], vcc
	s_nop 0
	v_cndmask_b32_e32 v146, 0, v0, vcc
	v_exp_f32_e64 v0, -v146
	v_add_f32_e32 v232, v232, v146
	v_xor_b32_e32 v144, 0x80000000, v232
	v_pk_add_f32 v[160:161], v[160:161], v[146:147] op_sel_hi:[1,0] neg_lo:[0,1] neg_hi:[0,1]
	v_pk_add_f32 v[162:163], v[162:163], v[146:147] op_sel_hi:[1,0] neg_lo:[0,1] neg_hi:[0,1]
	v_pk_add_f32 v[164:165], v[164:165], v[146:147] op_sel_hi:[1,0] neg_lo:[0,1] neg_hi:[0,1]
	v_pk_add_f32 v[166:167], v[166:167], v[146:147] op_sel_hi:[1,0] neg_lo:[0,1] neg_hi:[0,1]
	v_pk_add_f32 v[168:169], v[168:169], v[146:147] op_sel_hi:[1,0] neg_lo:[0,1] neg_hi:[0,1]
	v_pk_add_f32 v[170:171], v[170:171], v[146:147] op_sel_hi:[1,0] neg_lo:[0,1] neg_hi:[0,1]
	v_pk_add_f32 v[172:173], v[172:173], v[146:147] op_sel_hi:[1,0] neg_lo:[0,1] neg_hi:[0,1]
	v_pk_add_f32 v[174:175], v[174:175], v[146:147] op_sel_hi:[1,0] neg_lo:[0,1] neg_hi:[0,1]
	v_pk_mul_f32 v[142:143], v[142:143], v[0:1] op_sel_hi:[1,0]
	v_pk_mul_f32 v[140:141], v[140:141], v[0:1] op_sel_hi:[1,0]
	v_pk_mul_f32 v[138:139], v[138:139], v[0:1] op_sel_hi:[1,0]
	v_pk_mul_f32 v[136:137], v[136:137], v[0:1] op_sel_hi:[1,0]
	v_pk_mul_f32 v[134:135], v[134:135], v[0:1] op_sel_hi:[1,0]
	v_pk_mul_f32 v[132:133], v[132:133], v[0:1] op_sel_hi:[1,0]
	v_pk_mul_f32 v[130:131], v[130:131], v[0:1] op_sel_hi:[1,0]
	v_pk_mul_f32 v[128:129], v[128:129], v[0:1] op_sel_hi:[1,0]
	v_pk_mul_f32 v[126:127], v[126:127], v[0:1] op_sel_hi:[1,0]
	v_pk_mul_f32 v[124:125], v[124:125], v[0:1] op_sel_hi:[1,0]
	v_pk_mul_f32 v[122:123], v[122:123], v[0:1] op_sel_hi:[1,0]
	v_pk_mul_f32 v[120:121], v[120:121], v[0:1] op_sel_hi:[1,0]
	v_pk_mul_f32 v[118:119], v[118:119], v[0:1] op_sel_hi:[1,0]
	v_pk_mul_f32 v[116:117], v[116:117], v[0:1] op_sel_hi:[1,0]
	v_pk_mul_f32 v[114:115], v[114:115], v[0:1] op_sel_hi:[1,0]
	v_pk_mul_f32 v[112:113], v[112:113], v[0:1] op_sel_hi:[1,0]
	v_pk_mul_f32 v[110:111], v[110:111], v[0:1] op_sel_hi:[1,0]
	v_pk_mul_f32 v[108:109], v[108:109], v[0:1] op_sel_hi:[1,0]
	v_pk_mul_f32 v[106:107], v[106:107], v[0:1] op_sel_hi:[1,0]
	v_pk_mul_f32 v[104:105], v[104:105], v[0:1] op_sel_hi:[1,0]
	v_pk_mul_f32 v[102:103], v[102:103], v[0:1] op_sel_hi:[1,0]
	v_pk_mul_f32 v[100:101], v[100:101], v[0:1] op_sel_hi:[1,0]
	v_pk_mul_f32 v[98:99], v[98:99], v[0:1] op_sel_hi:[1,0]
	v_pk_mul_f32 v[96:97], v[96:97], v[0:1] op_sel_hi:[1,0]
	v_pk_mul_f32 v[94:95], v[94:95], v[0:1] op_sel_hi:[1,0]
	v_pk_mul_f32 v[92:93], v[92:93], v[0:1] op_sel_hi:[1,0]
	v_pk_mul_f32 v[90:91], v[90:91], v[0:1] op_sel_hi:[1,0]
	v_pk_mul_f32 v[88:89], v[88:89], v[0:1] op_sel_hi:[1,0]
	v_pk_mul_f32 v[86:87], v[86:87], v[0:1] op_sel_hi:[1,0]
	v_pk_mul_f32 v[84:85], v[84:85], v[0:1] op_sel_hi:[1,0]
	v_pk_mul_f32 v[82:83], v[82:83], v[0:1] op_sel_hi:[1,0]
	v_pk_mul_f32 v[80:81], v[80:81], v[0:1] op_sel_hi:[1,0]
	v_pk_mul_f32 v[78:79], v[78:79], v[0:1] op_sel_hi:[1,0]
	v_pk_mul_f32 v[76:77], v[76:77], v[0:1] op_sel_hi:[1,0]
	v_pk_mul_f32 v[74:75], v[74:75], v[0:1] op_sel_hi:[1,0]
	v_pk_mul_f32 v[72:73], v[72:73], v[0:1] op_sel_hi:[1,0]
	v_pk_mul_f32 v[70:71], v[70:71], v[0:1] op_sel_hi:[1,0]
	v_pk_mul_f32 v[68:69], v[68:69], v[0:1] op_sel_hi:[1,0]
	v_pk_mul_f32 v[66:67], v[66:67], v[0:1] op_sel_hi:[1,0]
	v_pk_mul_f32 v[64:65], v[64:65], v[0:1] op_sel_hi:[1,0]
	v_pk_mul_f32 v[62:63], v[62:63], v[0:1] op_sel_hi:[1,0]
	v_pk_mul_f32 v[60:61], v[60:61], v[0:1] op_sel_hi:[1,0]
	v_pk_mul_f32 v[58:59], v[58:59], v[0:1] op_sel_hi:[1,0]
	v_pk_mul_f32 v[56:57], v[56:57], v[0:1] op_sel_hi:[1,0]
	v_pk_mul_f32 v[54:55], v[54:55], v[0:1] op_sel_hi:[1,0]
	v_pk_mul_f32 v[52:53], v[52:53], v[0:1] op_sel_hi:[1,0]
	v_pk_mul_f32 v[50:51], v[50:51], v[0:1] op_sel_hi:[1,0]
	v_pk_mul_f32 v[48:49], v[48:49], v[0:1] op_sel_hi:[1,0]
	v_pk_mul_f32 v[46:47], v[46:47], v[0:1] op_sel_hi:[1,0]
	v_pk_mul_f32 v[44:45], v[44:45], v[0:1] op_sel_hi:[1,0]
	v_pk_mul_f32 v[42:43], v[42:43], v[0:1] op_sel_hi:[1,0]
	v_pk_mul_f32 v[40:41], v[40:41], v[0:1] op_sel_hi:[1,0]
	v_pk_mul_f32 v[38:39], v[38:39], v[0:1] op_sel_hi:[1,0]
	v_pk_mul_f32 v[36:37], v[36:37], v[0:1] op_sel_hi:[1,0]
	v_pk_mul_f32 v[34:35], v[34:35], v[0:1] op_sel_hi:[1,0]
	v_pk_mul_f32 v[32:33], v[32:33], v[0:1] op_sel_hi:[1,0]
	v_pk_mul_f32 v[30:31], v[30:31], v[0:1] op_sel_hi:[1,0]
	v_pk_mul_f32 v[28:29], v[28:29], v[0:1] op_sel_hi:[1,0]
	v_pk_mul_f32 v[26:27], v[26:27], v[0:1] op_sel_hi:[1,0]
	v_pk_mul_f32 v[24:25], v[24:25], v[0:1] op_sel_hi:[1,0]
	v_pk_mul_f32 v[22:23], v[22:23], v[0:1] op_sel_hi:[1,0]
	v_pk_mul_f32 v[20:21], v[20:21], v[0:1] op_sel_hi:[1,0]
	v_pk_mul_f32 v[18:19], v[18:19], v[0:1] op_sel_hi:[1,0]
	v_pk_mul_f32 v[16:17], v[16:17], v[0:1] op_sel_hi:[1,0]
	v_mov_b32_e32 v145, v144
	v_mov_b32_e32 v146, v144
	v_mov_b32_e32 v147, v144
	v_mov_b32_e32 v148, v144
	v_mov_b32_e32 v149, v144
	v_mov_b32_e32 v150, v144
	v_mov_b32_e32 v151, v144
	v_mov_b32_e32 v152, v144
	v_mov_b32_e32 v153, v144
	v_mov_b32_e32 v154, v144
	v_mov_b32_e32 v155, v144
	v_mov_b32_e32 v156, v144
	v_mov_b32_e32 v157, v144
	v_mov_b32_e32 v158, v144
	v_mov_b32_e32 v159, v144
	v_mul_f32_e32 v235, v235, v0
